# static priority, other half: waves 0-3 raised during the K-loops instead of waves 4-7 (flips deleted)
# speedup vs baseline: 1.0147x; 1.0042x over previous
.LBB0_169:
	s_ashr_i32 s51, s50, 31
	s_lshl_b64 s[12:13], s[50:51], 19
	s_add_u32 s52, s17, s12
	s_addc_u32 s53, s60, s13
	s_and_b64 s[12:13], s[40:41], exec
	s_cselect_b32 s3, s53, s9
	s_cselect_b32 s24, s52, s8
	s_ashr_i32 s49, s48, 31
	s_lshl_b64 s[12:13], s[48:49], 19
	s_add_u32 s54, s82, s12
	s_addc_u32 s55, s83, s13
	s_and_b64 s[12:13], s[40:41], exec
	s_cselect_b32 s25, s55, s11
	s_cselect_b32 s26, s54, s10
	s_add_u32 s8, s8, 0x40080
	s_addc_u32 s9, s9, 0
	s_add_u32 s27, s10, 0x100
	v_mov_b32_e32 v2, 0
	s_addc_u32 s28, s11, 0
	s_mov_b32 s29, -2
	v_mov_b64_e32 v[2:3], 0
	v_mov_b64_e32 v[4:5], 0
	v_mov_b64_e32 v[6:7], 0
	v_mov_b64_e32 v[8:9], 0
	v_mov_b64_e32 v[10:11], 0
	v_mov_b64_e32 v[12:13], 0
	v_mov_b64_e32 v[14:15], 0
	v_mov_b64_e32 v[16:17], 0
	v_mov_b64_e32 v[18:19], 0
	v_mov_b64_e32 v[20:21], 0
	v_mov_b64_e32 v[22:23], 0
	v_mov_b64_e32 v[24:25], 0
	v_mov_b64_e32 v[26:27], 0
	v_mov_b64_e32 v[28:29], 0
	v_mov_b64_e32 v[30:31], 0
	v_mov_b64_e32 v[32:33], 0
	v_mov_b64_e32 v[34:35], 0
	v_mov_b64_e32 v[36:37], 0
	v_mov_b64_e32 v[38:39], 0
	v_mov_b64_e32 v[40:41], 0
	v_mov_b64_e32 v[42:43], 0
	v_mov_b64_e32 v[44:45], 0
	v_mov_b64_e32 v[46:47], 0
	v_mov_b64_e32 v[48:49], 0
	v_mov_b64_e32 v[50:51], 0
	v_mov_b64_e32 v[52:53], 0
	v_mov_b64_e32 v[54:55], 0
	v_mov_b64_e32 v[56:57], 0
	v_mov_b64_e32 v[58:59], 0
	v_mov_b64_e32 v[60:61], 0
	v_mov_b64_e32 v[62:63], 0
	v_mov_b64_e32 v[64:65], 0
	v_mov_b64_e32 v[66:67], 0
	v_mov_b64_e32 v[68:69], 0
	v_mov_b64_e32 v[70:71], 0
	v_mov_b64_e32 v[72:73], 0
	v_mov_b64_e32 v[74:75], 0
	v_mov_b64_e32 v[76:77], 0
	v_mov_b64_e32 v[78:79], 0
	v_mov_b64_e32 v[80:81], 0
	v_mov_b64_e32 v[82:83], 0
	v_mov_b64_e32 v[84:85], 0
	v_mov_b64_e32 v[86:87], 0
	v_mov_b64_e32 v[88:89], 0
	v_mov_b64_e32 v[90:91], 0
	v_mov_b64_e32 v[92:93], 0
	v_mov_b64_e32 v[94:95], 0
	v_mov_b64_e32 v[96:97], 0
	v_mov_b64_e32 v[98:99], 0
	v_mov_b64_e32 v[100:101], 0
	v_mov_b64_e32 v[102:103], 0
	v_mov_b64_e32 v[104:105], 0
	v_mov_b64_e32 v[106:107], 0
	v_mov_b64_e32 v[108:109], 0
	v_mov_b64_e32 v[110:111], 0
	v_mov_b64_e32 v[112:113], 0
	v_mov_b64_e32 v[114:115], 0
	v_mov_b64_e32 v[116:117], 0
	v_mov_b64_e32 v[118:119], 0
	v_mov_b64_e32 v[120:121], 0
	v_mov_b64_e32 v[122:123], 0
	v_mov_b64_e32 v[124:125], 0
	v_mov_b64_e32 v[126:127], 0
	v_mov_b64_e32 v[128:129], 0
	s_cmp_eq_u32 s99, 0
	s_cbranch_scc0 .Lprio_LBB0_170
	s_setprio 1

.LBB0_545:
	s_ashr_i32 s47, s46, 31
	s_lshl_b64 s[14:15], s[46:47], 19
	s_add_u32 s48, s74, s14
	s_addc_u32 s49, s75, s15
	s_and_b64 s[14:15], s[40:41], exec
	s_cselect_b32 s14, s49, s53
	s_cselect_b32 s15, s48, s52
	s_ashr_i32 s45, s44, 31
	s_lshl_b64 s[24:25], s[44:45], 19
	s_add_u32 s50, s0, s24
	s_addc_u32 s51, s1, s25
	s_and_b64 s[24:25], s[40:41], exec
	s_cselect_b32 s26, s51, s11
	s_cselect_b32 s27, s50, s10
	s_lshl_b32 s24, s12, 8
	s_lshl_b32 s25, s13, 8
	s_or_b32 s28, s25, s63
	s_add_i32 s29, s24, s62
	s_add_u32 s12, s52, 0x40080
	s_addc_u32 s13, s53, 0
	v_mov_b32_e32 v2, v1
	v_mov_b32_e32 v3, v1
	s_add_u32 s45, s10, 0x100
	v_mov_b32_e32 v0, v1
	v_mov_b64_e32 v[6:7], v[2:3]
	v_mov_b64_e32 v[10:11], v[2:3]
	v_mov_b64_e32 v[22:23], v[2:3]
	v_mov_b64_e32 v[26:27], v[2:3]
	v_mov_b64_e32 v[38:39], v[2:3]
	v_mov_b64_e32 v[42:43], v[2:3]
	v_mov_b64_e32 v[54:55], v[2:3]
	v_mov_b64_e32 v[58:59], v[2:3]
	v_mov_b64_e32 v[14:15], v[2:3]
	v_mov_b64_e32 v[18:19], v[2:3]
	v_mov_b64_e32 v[30:31], v[2:3]
	v_mov_b64_e32 v[34:35], v[2:3]
	v_mov_b64_e32 v[46:47], v[2:3]
	v_mov_b64_e32 v[50:51], v[2:3]
	v_mov_b64_e32 v[62:63], v[2:3]
	v_mov_b64_e32 v[66:67], v[2:3]
	v_mov_b64_e32 v[70:71], v[2:3]
	v_mov_b64_e32 v[74:75], v[2:3]
	v_mov_b64_e32 v[86:87], v[2:3]
	v_mov_b64_e32 v[90:91], v[2:3]
	v_mov_b64_e32 v[102:103], v[2:3]
	v_mov_b64_e32 v[106:107], v[2:3]
	v_mov_b64_e32 v[118:119], v[2:3]
	v_mov_b64_e32 v[122:123], v[2:3]
	v_mov_b64_e32 v[78:79], v[2:3]
	v_mov_b64_e32 v[82:83], v[2:3]
	v_mov_b64_e32 v[94:95], v[2:3]
	v_mov_b64_e32 v[98:99], v[2:3]
	v_mov_b64_e32 v[110:111], v[2:3]
	v_mov_b64_e32 v[114:115], v[2:3]
	v_mov_b64_e32 v[126:127], v[2:3]
	v_mov_b64_e32 v[130:131], v[2:3]
	v_lshl_add_u64 v[154:155], s[12:13], 0, v[144:145]
	v_lshl_add_u64 v[156:157], s[12:13], 0, v[152:153]
	s_addc_u32 s47, s11, 0
	s_mov_b32 s68, -2
	s_mov_b64 s[10:11], 0
	v_mov_b64_e32 v[4:5], v[0:1]
	v_mov_b64_e32 v[8:9], v[0:1]
	v_mov_b64_e32 v[20:21], v[0:1]
	v_mov_b64_e32 v[24:25], v[0:1]
	v_mov_b64_e32 v[36:37], v[0:1]
	v_mov_b64_e32 v[40:41], v[0:1]
	v_mov_b64_e32 v[52:53], v[0:1]
	v_mov_b64_e32 v[56:57], v[0:1]
	v_mov_b64_e32 v[12:13], v[0:1]
	v_mov_b64_e32 v[16:17], v[0:1]
	v_mov_b64_e32 v[28:29], v[0:1]
	v_mov_b64_e32 v[32:33], v[0:1]
	v_mov_b64_e32 v[44:45], v[0:1]
	v_mov_b64_e32 v[48:49], v[0:1]
	v_mov_b64_e32 v[60:61], v[0:1]
	v_mov_b64_e32 v[64:65], v[0:1]
	v_mov_b64_e32 v[68:69], v[0:1]
	v_mov_b64_e32 v[72:73], v[0:1]
	v_mov_b64_e32 v[84:85], v[0:1]
	v_mov_b64_e32 v[88:89], v[0:1]
	v_mov_b64_e32 v[100:101], v[0:1]
	v_mov_b64_e32 v[104:105], v[0:1]
	v_mov_b64_e32 v[116:117], v[0:1]
	v_mov_b64_e32 v[120:121], v[0:1]
	v_mov_b64_e32 v[76:77], v[0:1]
	v_mov_b64_e32 v[80:81], v[0:1]
	v_mov_b64_e32 v[92:93], v[0:1]
	v_mov_b64_e32 v[96:97], v[0:1]
	v_mov_b64_e32 v[108:109], v[0:1]
	v_mov_b64_e32 v[112:113], v[0:1]
	v_mov_b64_e32 v[124:125], v[0:1]
	v_mov_b64_e32 v[128:129], v[0:1]
	s_cmp_eq_u32 s99, 0
	s_cbranch_scc0 .Lprio_LBB0_546
	s_setprio 1

.LBB0_639:
	s_ashr_i32 s49, s48, 31
	s_lshl_b64 s[14:15], s[48:49], 19
	v_readlane_b32 s11, v254, 16
	s_add_u32 s50, s11, s14
	v_readlane_b32 s11, v254, 17
	s_addc_u32 s51, s11, s15
	s_and_b64 s[14:15], s[42:43], exec
	s_cselect_b32 s11, s51, s13
	s_cselect_b32 s14, s50, s12
	s_ashr_i32 s47, s46, 31
	s_lshl_b64 s[24:25], s[46:47], 19
	s_add_u32 s52, s74, s24
	s_addc_u32 s53, s75, s25
	s_and_b64 s[24:25], s[42:43], exec
	s_cselect_b32 s15, s53, s55
	s_cselect_b32 s24, s52, s54
	s_add_u32 s12, s12, 0x40080
	s_addc_u32 s13, s13, 0
	s_add_u32 s25, s54, 0x100
	v_mov_b32_e32 v0, 0
	s_addc_u32 s26, s55, 0
	s_mov_b32 s27, -2
	s_waitcnt lgkmcnt(0)
	v_mov_b64_e32 v[0:1], 0
	v_mov_b64_e32 v[2:3], 0
	v_mov_b64_e32 v[4:5], 0
	v_mov_b64_e32 v[6:7], 0
	v_mov_b64_e32 v[8:9], 0
	v_mov_b64_e32 v[10:11], 0
	v_mov_b64_e32 v[12:13], 0
	v_mov_b64_e32 v[14:15], 0
	v_mov_b64_e32 v[16:17], 0
	v_mov_b64_e32 v[18:19], 0
	v_mov_b64_e32 v[20:21], 0
	v_mov_b64_e32 v[22:23], 0
	v_mov_b64_e32 v[24:25], 0
	v_mov_b64_e32 v[26:27], 0
	v_mov_b64_e32 v[28:29], 0
	v_mov_b64_e32 v[30:31], 0
	v_mov_b64_e32 v[32:33], 0
	v_mov_b64_e32 v[34:35], 0
	v_mov_b64_e32 v[36:37], 0
	v_mov_b64_e32 v[38:39], 0
	v_mov_b64_e32 v[40:41], 0
	v_mov_b64_e32 v[42:43], 0
	v_mov_b64_e32 v[44:45], 0
	v_mov_b64_e32 v[46:47], 0
	v_mov_b64_e32 v[48:49], 0
	v_mov_b64_e32 v[50:51], 0
	v_mov_b64_e32 v[52:53], 0
	v_mov_b64_e32 v[54:55], 0
	v_mov_b64_e32 v[56:57], 0
	v_mov_b64_e32 v[58:59], 0
	v_mov_b64_e32 v[60:61], 0
	v_mov_b64_e32 v[62:63], 0
	v_mov_b64_e32 v[64:65], 0
	v_mov_b64_e32 v[66:67], 0
	v_mov_b64_e32 v[68:69], 0
	v_mov_b64_e32 v[70:71], 0
	v_mov_b64_e32 v[72:73], 0
	v_mov_b64_e32 v[74:75], 0
	v_mov_b64_e32 v[76:77], 0
	v_mov_b64_e32 v[78:79], 0
	v_mov_b64_e32 v[80:81], 0
	v_mov_b64_e32 v[82:83], 0
	v_mov_b64_e32 v[84:85], 0
	v_mov_b64_e32 v[86:87], 0
	v_mov_b64_e32 v[88:89], 0
	v_mov_b64_e32 v[90:91], 0
	v_mov_b64_e32 v[92:93], 0
	v_mov_b64_e32 v[94:95], 0
	v_mov_b64_e32 v[96:97], 0
	v_mov_b64_e32 v[98:99], 0
	v_mov_b64_e32 v[100:101], 0
	v_mov_b64_e32 v[102:103], 0
	v_mov_b64_e32 v[104:105], 0
	v_mov_b64_e32 v[106:107], 0
	v_mov_b64_e32 v[108:109], 0
	v_mov_b64_e32 v[110:111], 0
	v_mov_b64_e32 v[112:113], 0
	v_mov_b64_e32 v[114:115], 0
	v_mov_b64_e32 v[116:117], 0
	v_mov_b64_e32 v[118:119], 0
	v_mov_b64_e32 v[120:121], 0
	v_mov_b64_e32 v[122:123], 0
	v_mov_b64_e32 v[124:125], 0
	v_mov_b64_e32 v[126:127], 0
	s_cmp_eq_u32 s99, 0
	s_cbranch_scc0 .Lprio_LBB0_640
	s_setprio 1

.LBB0_743:
	s_ashr_i32 s81, s80, 31
	s_lshl_b64 s[14:15], s[80:81], 19
	s_add_u32 s82, s96, s14
	s_addc_u32 s83, s97, s15
	s_and_b64 s[14:15], s[44:45], exec
	s_cselect_b32 s11, s83, s47
	s_cselect_b32 s14, s82, s46
	s_ashr_i32 s75, s74, 31
	s_lshl_b64 s[16:17], s[74:75], 19
	v_readlane_b32 s24, v254, 6
	v_readlane_b32 s25, v254, 7
	s_add_u32 s84, s24, s16
	s_addc_u32 s85, s25, s17
	s_and_b64 s[16:17], s[44:45], exec
	s_cselect_b32 s15, s85, s49
	s_cselect_b32 s16, s84, s48
	s_add_u32 s46, s46, 0x40080
	s_addc_u32 s47, s47, 0
	s_add_u32 s17, s48, 0x100
	v_mov_b32_e32 v64, 0
	s_addc_u32 s24, s49, 0
	s_mov_b32 s25, -2
	v_mov_b64_e32 v[0:1], 0
	v_mov_b64_e32 v[2:3], 0
	v_mov_b64_e32 v[4:5], 0
	v_mov_b64_e32 v[6:7], 0
	v_mov_b64_e32 v[8:9], 0
	v_mov_b64_e32 v[10:11], 0
	v_mov_b64_e32 v[12:13], 0
	v_mov_b64_e32 v[14:15], 0
	v_mov_b64_e32 v[16:17], 0
	v_mov_b64_e32 v[18:19], 0
	v_mov_b64_e32 v[20:21], 0
	v_mov_b64_e32 v[22:23], 0
	v_mov_b64_e32 v[24:25], 0
	v_mov_b64_e32 v[26:27], 0
	v_mov_b64_e32 v[28:29], 0
	v_mov_b64_e32 v[30:31], 0
	v_mov_b64_e32 v[32:33], 0
	v_mov_b64_e32 v[34:35], 0
	v_mov_b64_e32 v[36:37], 0
	v_mov_b64_e32 v[38:39], 0
	v_mov_b64_e32 v[40:41], 0
	v_mov_b64_e32 v[42:43], 0
	v_mov_b64_e32 v[44:45], 0
	v_mov_b64_e32 v[46:47], 0
	v_mov_b64_e32 v[48:49], 0
	v_mov_b64_e32 v[50:51], 0
	v_mov_b64_e32 v[52:53], 0
	v_mov_b64_e32 v[54:55], 0
	v_mov_b64_e32 v[56:57], 0
	v_mov_b64_e32 v[58:59], 0
	v_mov_b64_e32 v[60:61], 0
	v_mov_b64_e32 v[62:63], 0
	v_mov_b64_e32 v[64:65], 0
	v_mov_b64_e32 v[66:67], 0
	v_mov_b64_e32 v[68:69], 0
	v_mov_b64_e32 v[70:71], 0
	v_mov_b64_e32 v[72:73], 0
	v_mov_b64_e32 v[74:75], 0
	v_mov_b64_e32 v[76:77], 0
	v_mov_b64_e32 v[78:79], 0
	v_mov_b64_e32 v[96:97], 0
	v_mov_b64_e32 v[98:99], 0
	v_mov_b64_e32 v[100:101], 0
	v_mov_b64_e32 v[102:103], 0
	v_mov_b64_e32 v[104:105], 0
	v_mov_b64_e32 v[106:107], 0
	v_mov_b64_e32 v[108:109], 0
	v_mov_b64_e32 v[110:111], 0
	v_mov_b64_e32 v[112:113], 0
	v_mov_b64_e32 v[114:115], 0
	v_mov_b64_e32 v[116:117], 0
	v_mov_b64_e32 v[118:119], 0
	v_mov_b64_e32 v[120:121], 0
	v_mov_b64_e32 v[122:123], 0
	v_mov_b64_e32 v[124:125], 0
	v_mov_b64_e32 v[126:127], 0
	v_mov_b64_e32 v[136:137], 0
	v_mov_b64_e32 v[138:139], 0
	v_mov_b64_e32 v[140:141], 0
	v_mov_b64_e32 v[142:143], 0
	v_mov_b64_e32 v[144:145], 0
	v_mov_b64_e32 v[146:147], 0
	v_mov_b64_e32 v[148:149], 0
	v_mov_b64_e32 v[150:151], 0
	s_cmp_eq_u32 s99, 0
	s_cbranch_scc0 .Lprio_LBB0_744
	s_setprio 1

.LBB0_954:
	s_add_u32 s13, s46, 0x100
	v_mov_b32_e32 v0, 0
	s_addc_u32 s14, s47, 0
	s_mov_b32 s15, -2
	v_mov_b64_e32 v[0:1], 0
	v_mov_b64_e32 v[2:3], 0
	v_mov_b64_e32 v[4:5], 0
	v_mov_b64_e32 v[6:7], 0
	v_mov_b64_e32 v[8:9], 0
	v_mov_b64_e32 v[10:11], 0
	v_mov_b64_e32 v[12:13], 0
	v_mov_b64_e32 v[14:15], 0
	v_mov_b64_e32 v[16:17], 0
	v_mov_b64_e32 v[18:19], 0
	v_mov_b64_e32 v[20:21], 0
	v_mov_b64_e32 v[22:23], 0
	v_mov_b64_e32 v[24:25], 0
	v_mov_b64_e32 v[26:27], 0
	v_mov_b64_e32 v[28:29], 0
	v_mov_b64_e32 v[30:31], 0
	v_mov_b64_e32 v[32:33], 0
	v_mov_b64_e32 v[34:35], 0
	v_mov_b64_e32 v[36:37], 0
	v_mov_b64_e32 v[38:39], 0
	v_mov_b64_e32 v[40:41], 0
	v_mov_b64_e32 v[42:43], 0
	v_mov_b64_e32 v[44:45], 0
	v_mov_b64_e32 v[46:47], 0
	v_mov_b64_e32 v[48:49], 0
	v_mov_b64_e32 v[50:51], 0
	v_mov_b64_e32 v[52:53], 0
	v_mov_b64_e32 v[54:55], 0
	v_mov_b64_e32 v[56:57], 0
	v_mov_b64_e32 v[58:59], 0
	v_mov_b64_e32 v[60:61], 0
	v_mov_b64_e32 v[62:63], 0
	v_mov_b64_e32 v[64:65], 0
	v_mov_b64_e32 v[66:67], 0
	v_mov_b64_e32 v[68:69], 0
	v_mov_b64_e32 v[70:71], 0
	v_mov_b64_e32 v[72:73], 0
	v_mov_b64_e32 v[74:75], 0
	v_mov_b64_e32 v[76:77], 0
	v_mov_b64_e32 v[78:79], 0
	v_mov_b64_e32 v[80:81], 0
	v_mov_b64_e32 v[82:83], 0
	v_mov_b64_e32 v[84:85], 0
	v_mov_b64_e32 v[86:87], 0
	v_mov_b64_e32 v[88:89], 0
	v_mov_b64_e32 v[90:91], 0
	v_mov_b64_e32 v[92:93], 0
	v_mov_b64_e32 v[94:95], 0
	v_mov_b64_e32 v[96:97], 0
	v_mov_b64_e32 v[98:99], 0
	v_mov_b64_e32 v[100:101], 0
	v_mov_b64_e32 v[102:103], 0
	v_mov_b64_e32 v[104:105], 0
	v_mov_b64_e32 v[106:107], 0
	v_mov_b64_e32 v[108:109], 0
	v_mov_b64_e32 v[110:111], 0
	v_mov_b64_e32 v[112:113], 0
	v_mov_b64_e32 v[114:115], 0
	v_mov_b64_e32 v[116:117], 0
	v_mov_b64_e32 v[118:119], 0
	v_mov_b64_e32 v[120:121], 0
	v_mov_b64_e32 v[122:123], 0
	v_mov_b64_e32 v[124:125], 0
	v_mov_b64_e32 v[126:127], 0
	s_cmp_eq_u32 s99, 0
	s_cbranch_scc0 .Lprio_LBB0_955
	s_setprio 1
